# v43 plus GEMM accumulator zero-init with 64-bit moves (half the instructions per tile)
# speedup vs baseline: 1.0032x; 1.0032x over previous
;     __device__ __forceinline__ void init(f32x4 (&acc)[2][2][4][2], const Unit&, int, int, int, int) const {
; #pragma unroll
;         for (int a = 0; a < 2; ++a)
; #pragma unroll
;             for (int b = 0; b < 2; ++b)
; #pragma unroll
;                 for (int m = 0; m < 4; ++m)
; #pragma unroll
;                     for (int n = 0; n < 2; ++n) acc[a][b][m][n] = (f32x4){0.f, 0.f, 0.f, 0.f};
;     }
.LBB0_353:
	s_ashr_i32 s47, s46, 31
	s_lshl_b64 s[48:49], s[46:47], 20
	s_add_u32 s48, s68, s48
	s_addc_u32 s49, s69, s49
	s_and_b64 s[50:51], s[40:41], exec
	s_cselect_b32 s47, s49, s53
	s_cselect_b32 s67, s48, s52
	s_ashr_i32 s45, s44, 31
	s_lshl_b64 s[50:51], s[44:45], 20
	s_add_u32 s50, s34, s50
	s_addc_u32 s51, s33, s51
	s_and_b64 s[56:57], s[40:41], exec
	s_cselect_b32 s45, s51, s55
	s_cselect_b32 s70, s50, s54
	s_add_u32 s52, s52, 0x80080
	s_addc_u32 s53, s53, 0
	s_add_u32 s71, s54, 0x100
	v_mov_b32_e32 v2, 0
	s_addc_u32 s74, s55, 0
	s_mov_b32 s75, -2
	v_mov_b32_e32 v3, v2
	v_mov_b64_e32 v[4:5], v[2:3]
	v_mov_b64_e32 v[6:7], v[2:3]
	v_mov_b64_e32 v[8:9], v[2:3]
	v_mov_b64_e32 v[10:11], v[2:3]
	v_mov_b64_e32 v[12:13], v[2:3]
	v_mov_b64_e32 v[14:15], v[2:3]
	v_mov_b64_e32 v[16:17], v[2:3]
	v_mov_b64_e32 v[26:27], v[2:3]
	v_mov_b64_e32 v[28:29], v[2:3]
	v_mov_b64_e32 v[30:31], v[2:3]
	v_mov_b64_e32 v[32:33], v[2:3]
	v_mov_b64_e32 v[42:43], v[2:3]
	v_mov_b64_e32 v[44:45], v[2:3]
	v_mov_b64_e32 v[46:47], v[2:3]
	v_mov_b64_e32 v[48:49], v[2:3]
	v_mov_b64_e32 v[18:19], v[2:3]
	v_mov_b64_e32 v[20:21], v[2:3]
	v_mov_b64_e32 v[22:23], v[2:3]
	v_mov_b64_e32 v[24:25], v[2:3]
	v_mov_b64_e32 v[34:35], v[2:3]
	v_mov_b64_e32 v[36:37], v[2:3]
	v_mov_b64_e32 v[38:39], v[2:3]
	v_mov_b64_e32 v[40:41], v[2:3]
	v_mov_b64_e32 v[50:51], v[2:3]
	v_mov_b64_e32 v[52:53], v[2:3]
	v_mov_b64_e32 v[54:55], v[2:3]
	v_mov_b64_e32 v[56:57], v[2:3]
	v_mov_b64_e32 v[58:59], v[2:3]
	v_mov_b64_e32 v[60:61], v[2:3]
	v_mov_b64_e32 v[62:63], v[2:3]
	v_mov_b64_e32 v[64:65], v[2:3]
	v_mov_b64_e32 v[66:67], v[2:3]
	v_mov_b64_e32 v[68:69], v[2:3]
	v_mov_b64_e32 v[70:71], v[2:3]
	v_mov_b64_e32 v[72:73], v[2:3]
	v_mov_b64_e32 v[74:75], v[2:3]
	v_mov_b64_e32 v[76:77], v[2:3]
	v_mov_b64_e32 v[78:79], v[2:3]
	v_mov_b64_e32 v[80:81], v[2:3]
	v_mov_b64_e32 v[90:91], v[2:3]
	v_mov_b64_e32 v[92:93], v[2:3]
	v_mov_b64_e32 v[94:95], v[2:3]
	v_mov_b64_e32 v[96:97], v[2:3]
	v_mov_b64_e32 v[106:107], v[2:3]
	v_mov_b64_e32 v[108:109], v[2:3]
	v_mov_b64_e32 v[110:111], v[2:3]
	v_mov_b64_e32 v[112:113], v[2:3]
	v_mov_b64_e32 v[82:83], v[2:3]
	v_mov_b64_e32 v[84:85], v[2:3]
	v_mov_b64_e32 v[86:87], v[2:3]
	v_mov_b64_e32 v[88:89], v[2:3]
	v_mov_b64_e32 v[98:99], v[2:3]
	v_mov_b64_e32 v[100:101], v[2:3]
	v_mov_b64_e32 v[102:103], v[2:3]
	v_mov_b64_e32 v[104:105], v[2:3]
	v_mov_b64_e32 v[114:115], v[2:3]
	v_mov_b64_e32 v[116:117], v[2:3]
	v_mov_b64_e32 v[118:119], v[2:3]
	v_mov_b64_e32 v[120:121], v[2:3]
	v_mov_b64_e32 v[122:123], v[2:3]
	v_mov_b64_e32 v[124:125], v[2:3]
	v_mov_b64_e32 v[126:127], v[2:3]
	v_mov_b64_e32 v[128:129], v[2:3]

; __device__ __forceinline__ void gla_pre_phase(LAS unsigned char* lds, const bf16_t* proj, const bf16_t* hn, const bf16_t* wlr, const float* wa2, const float* ba, bf16_t* QT, bf16_t* KT, bf16_t* KH, float* DEC, int wg, int nwg, int tid) {
;     ...
;           f32x4 acc = (f32x4){0.f, 0.f, 0.f, 0.f};
.LBB0_659:
	v_mov_b32_e32 v2, 0
	s_mov_b64 s[62:63], 0
	v_mov_b32_e32 v3, v2
	v_mov_b64_e32 v[4:5], v[2:3]

;     __device__ __forceinline__ void init(f32x4 (&acc)[2][2][4][2], const Unit&, int, int, int, int) const {
; #pragma unroll
;         for (int a = 0; a < 2; ++a)
; #pragma unroll
;             for (int b = 0; b < 2; ++b)
; #pragma unroll
;                 for (int m = 0; m < 4; ++m)
; #pragma unroll
;                     for (int n = 0; n < 2; ++n) acc[a][b][m][n] = (f32x4){0.f, 0.f, 0.f, 0.f};
;     }
.LBB0_1088:
	s_ashr_i32 s43, s42, 31
	s_lshl_b64 s[44:45], s[42:43], 20
	s_add_u32 s44, s68, s44
	s_addc_u32 s45, s69, s45
	s_and_b64 s[50:51], s[40:41], exec
	s_cselect_b32 s43, s45, s21
	s_cselect_b32 s49, s44, s20
	s_ashr_i32 s67, s66, 31
	s_lshl_b64 s[50:51], s[66:67], 20
	s_add_u32 s50, s46, s50
	s_addc_u32 s51, s47, s51
	s_and_b64 s[74:75], s[40:41], exec
	s_cselect_b32 s67, s51, s53
	s_cselect_b32 s71, s50, s52
	s_add_u32 s20, s20, 0x80080
	s_addc_u32 s21, s21, 0
	s_add_u32 s74, s52, 0x100
	v_mov_b32_e32 v2, 0
	s_addc_u32 s75, s53, 0
	s_mov_b32 s76, -2
	v_mov_b32_e32 v3, v2
	v_mov_b64_e32 v[4:5], v[2:3]
	v_mov_b64_e32 v[10:11], v[2:3]
	v_mov_b64_e32 v[12:13], v[2:3]
	v_mov_b64_e32 v[18:19], v[2:3]
	v_mov_b64_e32 v[20:21], v[2:3]
	v_mov_b64_e32 v[26:27], v[2:3]
	v_mov_b64_e32 v[28:29], v[2:3]
	v_mov_b64_e32 v[34:35], v[2:3]
	v_mov_b64_e32 v[36:37], v[2:3]
	v_mov_b64_e32 v[42:43], v[2:3]
	v_mov_b64_e32 v[44:45], v[2:3]
	v_mov_b64_e32 v[50:51], v[2:3]
	v_mov_b64_e32 v[52:53], v[2:3]
	v_mov_b64_e32 v[58:59], v[2:3]
	v_mov_b64_e32 v[60:61], v[2:3]
	v_mov_b64_e32 v[6:7], v[2:3]
	v_mov_b64_e32 v[8:9], v[2:3]
	v_mov_b64_e32 v[14:15], v[2:3]
	v_mov_b64_e32 v[16:17], v[2:3]
	v_mov_b64_e32 v[22:23], v[2:3]
	v_mov_b64_e32 v[24:25], v[2:3]
	v_mov_b64_e32 v[30:31], v[2:3]
	v_mov_b64_e32 v[32:33], v[2:3]
	v_mov_b64_e32 v[38:39], v[2:3]
	v_mov_b64_e32 v[40:41], v[2:3]
	v_mov_b64_e32 v[46:47], v[2:3]
	v_mov_b64_e32 v[48:49], v[2:3]
	v_mov_b64_e32 v[54:55], v[2:3]
	v_mov_b64_e32 v[56:57], v[2:3]
	v_mov_b64_e32 v[62:63], v[2:3]
	v_mov_b64_e32 v[64:65], v[2:3]
	v_mov_b64_e32 v[66:67], v[2:3]
	v_mov_b64_e32 v[68:69], v[2:3]
	v_mov_b64_e32 v[74:75], v[2:3]
	v_mov_b64_e32 v[76:77], v[2:3]
	v_mov_b64_e32 v[82:83], v[2:3]
	v_mov_b64_e32 v[84:85], v[2:3]
	v_mov_b64_e32 v[90:91], v[2:3]
	v_mov_b64_e32 v[92:93], v[2:3]
	v_mov_b64_e32 v[98:99], v[2:3]
	v_mov_b64_e32 v[100:101], v[2:3]
	v_mov_b64_e32 v[106:107], v[2:3]
	v_mov_b64_e32 v[108:109], v[2:3]
	v_mov_b64_e32 v[114:115], v[2:3]
	v_mov_b64_e32 v[116:117], v[2:3]
	v_mov_b64_e32 v[122:123], v[2:3]
	v_mov_b64_e32 v[124:125], v[2:3]
	v_mov_b64_e32 v[70:71], v[2:3]
	v_mov_b64_e32 v[72:73], v[2:3]
	v_mov_b64_e32 v[78:79], v[2:3]
	v_mov_b64_e32 v[80:81], v[2:3]
	v_mov_b64_e32 v[86:87], v[2:3]
	v_mov_b64_e32 v[88:89], v[2:3]
	v_mov_b64_e32 v[94:95], v[2:3]
	v_mov_b64_e32 v[96:97], v[2:3]
	v_mov_b64_e32 v[102:103], v[2:3]
	v_mov_b64_e32 v[104:105], v[2:3]
	v_mov_b64_e32 v[110:111], v[2:3]
	v_mov_b64_e32 v[112:113], v[2:3]
	v_mov_b64_e32 v[118:119], v[2:3]
	v_mov_b64_e32 v[120:121], v[2:3]
	v_mov_b64_e32 v[126:127], v[2:3]
	v_mov_b64_e32 v[128:129], v[2:3]
